# HGRN/mLSTM chunk scans via DPP row shifts + readlane cross-row (was 6 ds_bpermute levels), byte count kept equal mod 8 so later loops keep their placement
# speedup vs baseline: 1.0032x; 1.0032x over previous
; template <int MX, bool OUT>
; DI void rec_chunk(const Params& p, int l, int b, int h, int dir, int T0, unsigned char* smem, f32x4 (&St)[4], float& nst, float& dtot, int tid, const RecRaw& raw) {
;     ...
;   if (MX == 1) {
;     if (w == 0) {
;       float x = CUM[lane * 64];
; #pragma unroll
;       for (int o = 1; o < 64; o <<= 1) {
;         const float y = dir == 0 ? __shfl_up(x, o) : __shfl_down(x, o);
;         const bool ok = dir == 0 ? (lane >= o) : (lane + o < 64);
;         x += ok ? y : 0.f;
;       }
;       CUM[lane * 64] = x;
;     }
;     __syncthreads();
.Lsc1_done:
	s_nop 0
	ds_write_b32 v150, v65

; template <int MX, bool OUT>
; DI void rec_chunk(const Params& p, int l, int b, int h, int dir, int T0, unsigned char* smem, f32x4 (&St)[4], float& nst, float& dtot, int tid, const RecRaw& raw) {
;     ...
;   if (MX == 1) {
;     if (w == 0) {
;       float x = CUM[lane * 64];
; #pragma unroll
;       for (int o = 1; o < 64; o <<= 1) {
;         const float y = dir == 0 ? __shfl_up(x, o) : __shfl_down(x, o);
;         const bool ok = dir == 0 ? (lane >= o) : (lane + o < 64);
;         x += ok ? y : 0.f;
;       }
;       CUM[lane * 64] = x;
;     }
;     __syncthreads();
.Lsc2_done:
	s_nop 0
	ds_write_b32 v154, v65
